# opt30: opt26 + every hot loop head (8 GEMM K-loops, 2 attention loops) placed on a 64-byte boundary with s_nop fill
# speedup vs baseline: 1.0009x; 1.0009x over previous
; template <class Epi>
; __device__ __forceinline__ void gemm_phase(LAS unsigned char* lds, const Gemm g, const StaticOrder& S, const Epi& E) {
;     ...
;         const bool has_next = S.next(ui + 1, nxt);
;         const char* nA = has_next ? (const char*)g.A + (size_t)nxt.pm * tsA : cA; const char* nB = has_next ? (const char*)g.Bt + (size_t)nxt.pn * tsB : cB;
;         for (int t = 0; t < nt; t += 2) {
;             const bool last = (t == nt - 2);
;             if constexpr (Epi::HAS_MID) { if (t == nt1) E.mid(acc, cur, wr, wc, fr, fq); }
;             const char* a1 = cA + ((Epi::HAS_MID && t >= nt1) ? dA2 : 0) + (size_t)(t + 1) * kstep;
;             const char* a2 = last ? nA : cA + ((Epi::HAS_MID && t + 2 >= nt1) ? dA2 : 0) + (size_t)(t + 2) * kstep; const char* b2 = last ? nB : cB + ((Epi::HAS_MID && t + 2 >= nt1) ? dB2 : 0) + (size_t)(t + 2) * kstep;
;     ...
; #pragma unroll
;         for (int a = 0; a < 2; ++a)
; #pragma unroll
;             for (int b = 0; b < 2; ++b)
; #pragma unroll
;                 for (int m = 0; m < 4; ++m)
; #pragma unroll
;                     for (int n = 0; n < 2; ++n) acc[a][b][m][n] = (f32x4){0.f, 0.f, 0.f, 0.f};
;         cur = nxt; cA = nA; cB = nB; ++ui;
.LBB0_213:
	s_ashr_i32 s13, s12, 31
	s_lshl_b64 s[6:7], s[12:13], 19
	s_add_u32 s14, s70, s6
	s_addc_u32 s15, s71, s7
	s_and_b64 s[6:7], s[4:5], exec
	s_cselect_b32 s6, s15, s59
	s_cselect_b32 s7, s14, s58
	s_ashr_i32 s11, s10, 31
	s_lshl_b64 s[36:37], s[10:11], 19
	v_readlane_b32 s11, v254, 25
	s_add_u32 s42, s11, s36
	v_readlane_b32 s11, v254, 26
	s_addc_u32 s43, s11, s37
	s_and_b64 s[36:37], s[4:5], exec
	s_cselect_b32 s11, s43, s61
	s_cselect_b32 s13, s42, s60
	s_add_u32 s58, s58, 0x40080
	s_addc_u32 s59, s59, 0
	s_add_u32 s35, s60, 0x100
	v_mov_b32_e32 v0, 0
	s_addc_u32 s36, s61, 0
	s_mov_b32 s37, -2
	v_mov_b32_e32 v1, v0
	v_mov_b32_e32 v2, v0
	v_mov_b32_e32 v3, v0
	v_mov_b32_e32 v4, v0
	v_mov_b32_e32 v5, v0
	v_mov_b32_e32 v6, v0
	v_mov_b32_e32 v7, v0
	v_mov_b32_e32 v16, v0
	v_mov_b32_e32 v17, v0
	v_mov_b32_e32 v18, v0
	v_mov_b32_e32 v19, v0
	v_mov_b32_e32 v20, v0
	v_mov_b32_e32 v21, v0
	v_mov_b32_e32 v22, v0
	v_mov_b32_e32 v23, v0
	v_mov_b32_e32 v32, v0
	v_mov_b32_e32 v33, v0
	v_mov_b32_e32 v34, v0
	v_mov_b32_e32 v35, v0
	v_mov_b32_e32 v36, v0
	v_mov_b32_e32 v37, v0
	v_mov_b32_e32 v38, v0
	v_mov_b32_e32 v39, v0
	v_mov_b32_e32 v48, v0
	v_mov_b32_e32 v49, v0
	v_mov_b32_e32 v50, v0
	v_mov_b32_e32 v51, v0
	v_mov_b32_e32 v52, v0
	v_mov_b32_e32 v53, v0
	v_mov_b32_e32 v54, v0
	v_mov_b32_e32 v55, v0
	v_mov_b32_e32 v8, v0
	v_mov_b32_e32 v9, v0
	v_mov_b32_e32 v10, v0
	v_mov_b32_e32 v11, v0
	v_mov_b32_e32 v12, v0
	v_mov_b32_e32 v13, v0
	v_mov_b32_e32 v14, v0
	v_mov_b32_e32 v15, v0
	v_mov_b32_e32 v24, v0
	v_mov_b32_e32 v25, v0
	v_mov_b32_e32 v26, v0
	v_mov_b32_e32 v27, v0
	v_mov_b32_e32 v28, v0
	v_mov_b32_e32 v29, v0
	v_mov_b32_e32 v30, v0
	v_mov_b32_e32 v31, v0
	v_mov_b32_e32 v40, v0
	v_mov_b32_e32 v41, v0
	v_mov_b32_e32 v42, v0
	v_mov_b32_e32 v43, v0
	v_mov_b32_e32 v44, v0
	v_mov_b32_e32 v45, v0
	v_mov_b32_e32 v46, v0
	v_mov_b32_e32 v47, v0
	v_mov_b32_e32 v56, v0
	v_mov_b32_e32 v57, v0
	v_mov_b32_e32 v58, v0
	v_mov_b32_e32 v59, v0
	v_mov_b32_e32 v60, v0
	v_mov_b32_e32 v61, v0
	v_mov_b32_e32 v62, v0
	v_mov_b32_e32 v63, v0
	v_mov_b32_e32 v64, v0
	v_mov_b32_e32 v65, v0
	v_mov_b32_e32 v66, v0
	v_mov_b32_e32 v67, v0
	v_mov_b32_e32 v68, v0
	v_mov_b32_e32 v69, v0
	v_mov_b32_e32 v70, v0
	v_mov_b32_e32 v71, v0
	v_mov_b32_e32 v80, v0
	v_mov_b32_e32 v81, v0
	v_mov_b32_e32 v82, v0
	v_mov_b32_e32 v83, v0
	v_mov_b32_e32 v84, v0
	v_mov_b32_e32 v85, v0
	v_mov_b32_e32 v86, v0
	v_mov_b32_e32 v87, v0
	v_mov_b32_e32 v96, v0
	v_mov_b32_e32 v97, v0
	v_mov_b32_e32 v98, v0
	v_mov_b32_e32 v99, v0
	v_mov_b32_e32 v100, v0
	v_mov_b32_e32 v101, v0
	v_mov_b32_e32 v102, v0
	v_mov_b32_e32 v103, v0
	v_mov_b32_e32 v112, v0
	v_mov_b32_e32 v113, v0
	v_mov_b32_e32 v114, v0
	v_mov_b32_e32 v115, v0
	v_mov_b32_e32 v116, v0
	v_mov_b32_e32 v117, v0
	v_mov_b32_e32 v118, v0
	v_mov_b32_e32 v119, v0
	v_mov_b32_e32 v72, v0
	v_mov_b32_e32 v73, v0
	v_mov_b32_e32 v74, v0
	v_mov_b32_e32 v75, v0
	v_mov_b32_e32 v76, v0
	v_mov_b32_e32 v77, v0
	v_mov_b32_e32 v78, v0
	v_mov_b32_e32 v79, v0
	v_mov_b32_e32 v88, v0
	v_mov_b32_e32 v89, v0
	v_mov_b32_e32 v90, v0
	v_mov_b32_e32 v91, v0
	v_mov_b32_e32 v92, v0
	v_mov_b32_e32 v93, v0
	v_mov_b32_e32 v94, v0
	v_mov_b32_e32 v95, v0
	v_mov_b32_e32 v104, v0
	v_mov_b32_e32 v105, v0
	v_mov_b32_e32 v106, v0
	v_mov_b32_e32 v107, v0
	v_mov_b32_e32 v108, v0
	v_mov_b32_e32 v109, v0
	v_mov_b32_e32 v110, v0
	v_mov_b32_e32 v111, v0
	v_mov_b32_e32 v120, v0
	v_mov_b32_e32 v121, v0
	v_mov_b32_e32 v122, v0
	v_mov_b32_e32 v123, v0
	v_mov_b32_e32 v124, v0
	v_mov_b32_e32 v125, v0
	v_mov_b32_e32 v126, v0
	v_mov_b32_e32 v127, v0
	.p2alignl 6, 3212836864

; template <class Epi>
; __device__ __forceinline__ void gemm_phase(LAS unsigned char* lds, const Gemm g, const StaticOrder& S, const Epi& E) {
;     ...
; #pragma unroll
;         for (int a = 0; a < 2; ++a)
; #pragma unroll
;             for (int b = 0; b < 2; ++b)
; #pragma unroll
;                 for (int m = 0; m < 4; ++m)
; #pragma unroll
;                     for (int n = 0; n < 2; ++n) acc[a][b][m][n] = (f32x4){0.f, 0.f, 0.f, 0.f};
;         cur = nxt; cA = nA; cB = nB; ++ui;
.LBB0_295:
	s_add_u32 s6, s60, 0x100
	v_mov_b32_e32 v0, 0
	s_addc_u32 s7, s61, 0
	s_mov_b32 s34, -2
	s_waitcnt lgkmcnt(0)
	v_mov_b32_e32 v1, v0
	v_mov_b32_e32 v2, v0
	v_mov_b32_e32 v3, v0
	v_mov_b32_e32 v4, v0
	v_mov_b32_e32 v5, v0
	v_mov_b32_e32 v6, v0
	v_mov_b32_e32 v7, v0
	v_mov_b32_e32 v16, v0
	v_mov_b32_e32 v17, v0
	v_mov_b32_e32 v18, v0
	v_mov_b32_e32 v19, v0
	v_mov_b32_e32 v20, v0
	v_mov_b32_e32 v21, v0
	v_mov_b32_e32 v22, v0
	v_mov_b32_e32 v23, v0
	v_mov_b32_e32 v32, v0
	v_mov_b32_e32 v33, v0
	v_mov_b32_e32 v34, v0
	v_mov_b32_e32 v35, v0
	v_mov_b32_e32 v36, v0
	v_mov_b32_e32 v37, v0
	v_mov_b32_e32 v38, v0
	v_mov_b32_e32 v39, v0
	v_mov_b32_e32 v48, v0
	v_mov_b32_e32 v49, v0
	v_mov_b32_e32 v50, v0
	v_mov_b32_e32 v51, v0
	v_mov_b32_e32 v52, v0
	v_mov_b32_e32 v53, v0
	v_mov_b32_e32 v54, v0
	v_mov_b32_e32 v55, v0
	v_mov_b32_e32 v8, v0
	v_mov_b32_e32 v9, v0
	v_mov_b32_e32 v10, v0
	v_mov_b32_e32 v11, v0
	v_mov_b32_e32 v12, v0
	v_mov_b32_e32 v13, v0
	v_mov_b32_e32 v14, v0
	v_mov_b32_e32 v15, v0
	v_mov_b32_e32 v24, v0
	v_mov_b32_e32 v25, v0
	v_mov_b32_e32 v26, v0
	v_mov_b32_e32 v27, v0
	v_mov_b32_e32 v28, v0
	v_mov_b32_e32 v29, v0
	v_mov_b32_e32 v30, v0
	v_mov_b32_e32 v31, v0
	v_mov_b32_e32 v40, v0
	v_mov_b32_e32 v41, v0
	v_mov_b32_e32 v42, v0
	v_mov_b32_e32 v43, v0
	v_mov_b32_e32 v44, v0
	v_mov_b32_e32 v45, v0
	v_mov_b32_e32 v46, v0
	v_mov_b32_e32 v47, v0
	v_mov_b32_e32 v56, v0
	v_mov_b32_e32 v57, v0
	v_mov_b32_e32 v58, v0
	v_mov_b32_e32 v59, v0
	v_mov_b32_e32 v60, v0
	v_mov_b32_e32 v61, v0
	v_mov_b32_e32 v62, v0
	v_mov_b32_e32 v63, v0
	v_mov_b32_e32 v64, v0
	v_mov_b32_e32 v65, v0
	v_mov_b32_e32 v66, v0
	v_mov_b32_e32 v67, v0
	v_mov_b32_e32 v68, v0
	v_mov_b32_e32 v69, v0
	v_mov_b32_e32 v70, v0
	v_mov_b32_e32 v71, v0
	v_mov_b32_e32 v80, v0
	v_mov_b32_e32 v81, v0
	v_mov_b32_e32 v82, v0
	v_mov_b32_e32 v83, v0
	v_mov_b32_e32 v84, v0
	v_mov_b32_e32 v85, v0
	v_mov_b32_e32 v86, v0
	v_mov_b32_e32 v87, v0
	v_mov_b32_e32 v96, v0
	v_mov_b32_e32 v97, v0
	v_mov_b32_e32 v98, v0
	v_mov_b32_e32 v99, v0
	v_mov_b32_e32 v100, v0
	v_mov_b32_e32 v101, v0
	v_mov_b32_e32 v102, v0
	v_mov_b32_e32 v103, v0
	v_mov_b32_e32 v112, v0
	v_mov_b32_e32 v113, v0
	v_mov_b32_e32 v114, v0
	v_mov_b32_e32 v115, v0
	v_mov_b32_e32 v116, v0
	v_mov_b32_e32 v117, v0
	v_mov_b32_e32 v118, v0
	v_mov_b32_e32 v119, v0
	v_mov_b32_e32 v72, v0
	v_mov_b32_e32 v73, v0
	v_mov_b32_e32 v74, v0
	v_mov_b32_e32 v75, v0
	v_mov_b32_e32 v76, v0
	v_mov_b32_e32 v77, v0
	v_mov_b32_e32 v78, v0
	v_mov_b32_e32 v79, v0
	v_mov_b32_e32 v88, v0
	v_mov_b32_e32 v89, v0
	v_mov_b32_e32 v90, v0
	v_mov_b32_e32 v91, v0
	v_mov_b32_e32 v92, v0
	v_mov_b32_e32 v93, v0
	v_mov_b32_e32 v94, v0
	v_mov_b32_e32 v95, v0
	v_mov_b32_e32 v104, v0
	v_mov_b32_e32 v105, v0
	v_mov_b32_e32 v106, v0
	v_mov_b32_e32 v107, v0
	v_mov_b32_e32 v108, v0
	v_mov_b32_e32 v109, v0
	v_mov_b32_e32 v110, v0
	v_mov_b32_e32 v111, v0
	v_mov_b32_e32 v120, v0
	v_mov_b32_e32 v121, v0
	v_mov_b32_e32 v122, v0
	v_mov_b32_e32 v123, v0
	v_mov_b32_e32 v124, v0
	v_mov_b32_e32 v125, v0
	v_mov_b32_e32 v126, v0
	v_mov_b32_e32 v127, v0
	.p2alignl 6, 3212836864

; template <class Epi>
; __device__ __forceinline__ void gemm_phase(LAS unsigned char* lds, const Gemm g, const StaticOrder& S, const Epi& E) {
;     ...
;         const bool has_next = S.next(ui + 1, nxt);
;         const char* nA = has_next ? (const char*)g.A + (size_t)nxt.pm * tsA : cA; const char* nB = has_next ? (const char*)g.Bt + (size_t)nxt.pn * tsB : cB;
;         for (int t = 0; t < nt; t += 2) {
;             const bool last = (t == nt - 2);
;             if constexpr (Epi::HAS_MID) { if (t == nt1) E.mid(acc, cur, wr, wc, fr, fq); }
;             const char* a1 = cA + ((Epi::HAS_MID && t >= nt1) ? dA2 : 0) + (size_t)(t + 1) * kstep;
;             const char* a2 = last ? nA : cA + ((Epi::HAS_MID && t + 2 >= nt1) ? dA2 : 0) + (size_t)(t + 2) * kstep; const char* b2 = last ? nB : cB + ((Epi::HAS_MID && t + 2 >= nt1) ? dB2 : 0) + (size_t)(t + 2) * kstep;
;     ...
; #pragma unroll
;         for (int a = 0; a < 2; ++a)
; #pragma unroll
;             for (int b = 0; b < 2; ++b)
; #pragma unroll
;                 for (int m = 0; m < 4; ++m)
; #pragma unroll
;                     for (int n = 0; n < 2; ++n) acc[a][b][m][n] = (f32x4){0.f, 0.f, 0.f, 0.f};
;         cur = nxt; cA = nA; cB = nB; ++ui;
.LBB0_413:
	s_ashr_i32 s81, s80, 31
	s_lshl_b64 s[2:3], s[80:81], 19
	s_add_u32 s82, s70, s2
	s_addc_u32 s83, s71, s3
	s_and_b64 s[2:3], s[8:9], exec
	s_cselect_b32 s0, s83, s11
	s_cselect_b32 s2, s82, s10
	s_ashr_i32 s79, s78, 31
	s_lshl_b64 s[6:7], s[78:79], 19
	s_add_u32 s84, s56, s6
	s_addc_u32 s85, s57, s7
	s_and_b64 s[6:7], s[8:9], exec
	s_cselect_b32 s3, s85, s13
	s_cselect_b32 s6, s84, s12
	s_add_u32 s10, s10, 0x40080
	s_addc_u32 s11, s11, 0
	s_add_u32 s7, s12, 0x100
	v_mov_b32_e32 v0, 0
	s_addc_u32 s15, s13, 0
	s_mov_b32 s17, -2
	v_mov_b32_e32 v1, v0
	v_mov_b32_e32 v2, v0
	v_mov_b32_e32 v3, v0
	v_mov_b32_e32 v4, v0
	v_mov_b32_e32 v5, v0
	v_mov_b32_e32 v6, v0
	v_mov_b32_e32 v7, v0
	v_mov_b32_e32 v16, v0
	v_mov_b32_e32 v17, v0
	v_mov_b32_e32 v18, v0
	v_mov_b32_e32 v19, v0
	v_mov_b32_e32 v20, v0
	v_mov_b32_e32 v21, v0
	v_mov_b32_e32 v22, v0
	v_mov_b32_e32 v23, v0
	v_mov_b32_e32 v32, v0
	v_mov_b32_e32 v33, v0
	v_mov_b32_e32 v34, v0
	v_mov_b32_e32 v35, v0
	v_mov_b32_e32 v36, v0
	v_mov_b32_e32 v37, v0
	v_mov_b32_e32 v38, v0
	v_mov_b32_e32 v39, v0
	v_mov_b32_e32 v48, v0
	v_mov_b32_e32 v49, v0
	v_mov_b32_e32 v50, v0
	v_mov_b32_e32 v51, v0
	v_mov_b32_e32 v52, v0
	v_mov_b32_e32 v53, v0
	v_mov_b32_e32 v54, v0
	v_mov_b32_e32 v55, v0
	v_mov_b32_e32 v8, v0
	v_mov_b32_e32 v9, v0
	v_mov_b32_e32 v10, v0
	v_mov_b32_e32 v11, v0
	v_mov_b32_e32 v12, v0
	v_mov_b32_e32 v13, v0
	v_mov_b32_e32 v14, v0
	v_mov_b32_e32 v15, v0
	v_mov_b32_e32 v24, v0
	v_mov_b32_e32 v25, v0
	v_mov_b32_e32 v26, v0
	v_mov_b32_e32 v27, v0
	v_mov_b32_e32 v28, v0
	v_mov_b32_e32 v29, v0
	v_mov_b32_e32 v30, v0
	v_mov_b32_e32 v31, v0
	v_mov_b32_e32 v40, v0
	v_mov_b32_e32 v41, v0
	v_mov_b32_e32 v42, v0
	v_mov_b32_e32 v43, v0
	v_mov_b32_e32 v44, v0
	v_mov_b32_e32 v45, v0
	v_mov_b32_e32 v46, v0
	v_mov_b32_e32 v47, v0
	v_mov_b32_e32 v56, v0
	v_mov_b32_e32 v57, v0
	v_mov_b32_e32 v58, v0
	v_mov_b32_e32 v59, v0
	v_mov_b32_e32 v60, v0
	v_mov_b32_e32 v61, v0
	v_mov_b32_e32 v62, v0
	v_mov_b32_e32 v63, v0
	v_mov_b32_e32 v64, v0
	v_mov_b32_e32 v65, v0
	v_mov_b32_e32 v66, v0
	v_mov_b32_e32 v67, v0
	v_mov_b32_e32 v68, v0
	v_mov_b32_e32 v69, v0
	v_mov_b32_e32 v70, v0
	v_mov_b32_e32 v71, v0
	v_mov_b32_e32 v80, v0
	v_mov_b32_e32 v81, v0
	v_mov_b32_e32 v82, v0
	v_mov_b32_e32 v83, v0
	v_mov_b32_e32 v84, v0
	v_mov_b32_e32 v85, v0
	v_mov_b32_e32 v86, v0
	v_mov_b32_e32 v87, v0
	v_mov_b32_e32 v96, v0
	v_mov_b32_e32 v97, v0
	v_mov_b32_e32 v98, v0
	v_mov_b32_e32 v99, v0
	v_mov_b32_e32 v100, v0
	v_mov_b32_e32 v101, v0
	v_mov_b32_e32 v102, v0
	v_mov_b32_e32 v103, v0
	v_mov_b32_e32 v112, v0
	v_mov_b32_e32 v113, v0
	v_mov_b32_e32 v114, v0
	v_mov_b32_e32 v115, v0
	v_mov_b32_e32 v116, v0
	v_mov_b32_e32 v117, v0
	v_mov_b32_e32 v118, v0
	v_mov_b32_e32 v119, v0
	v_mov_b32_e32 v72, v0
	v_mov_b32_e32 v73, v0
	v_mov_b32_e32 v74, v0
	v_mov_b32_e32 v75, v0
	v_mov_b32_e32 v76, v0
	v_mov_b32_e32 v77, v0
	v_mov_b32_e32 v78, v0
	v_mov_b32_e32 v79, v0
	v_mov_b32_e32 v88, v0
	v_mov_b32_e32 v89, v0
	v_mov_b32_e32 v90, v0
	v_mov_b32_e32 v91, v0
	v_mov_b32_e32 v92, v0
	v_mov_b32_e32 v93, v0
	v_mov_b32_e32 v94, v0
	v_mov_b32_e32 v95, v0
	v_mov_b32_e32 v104, v0
	v_mov_b32_e32 v105, v0
	v_mov_b32_e32 v106, v0
	v_mov_b32_e32 v107, v0
	v_mov_b32_e32 v108, v0
	v_mov_b32_e32 v109, v0
	v_mov_b32_e32 v110, v0
	v_mov_b32_e32 v111, v0
	v_mov_b32_e32 v120, v0
	v_mov_b32_e32 v121, v0
	v_mov_b32_e32 v122, v0
	v_mov_b32_e32 v123, v0
	v_mov_b32_e32 v124, v0
	v_mov_b32_e32 v125, v0
	v_mov_b32_e32 v126, v0
	v_mov_b32_e32 v127, v0
	.p2alignl 6, 3212836864

; template <class Epi>
; __device__ __forceinline__ void gemm_phase(LAS unsigned char* lds, const Gemm g, const StaticOrder& S, const Epi& E) {
;     ...
;         const bool has_next = S.next(ui + 1, nxt);
;         const char* nA = has_next ? (const char*)g.A + (size_t)nxt.pm * tsA : cA; const char* nB = has_next ? (const char*)g.Bt + (size_t)nxt.pn * tsB : cB;
;         for (int t = 0; t < nt; t += 2) {
;             const bool last = (t == nt - 2);
;             if constexpr (Epi::HAS_MID) { if (t == nt1) E.mid(acc, cur, wr, wc, fr, fq); }
;             const char* a1 = cA + ((Epi::HAS_MID && t >= nt1) ? dA2 : 0) + (size_t)(t + 1) * kstep;
;             const char* a2 = last ? nA : cA + ((Epi::HAS_MID && t + 2 >= nt1) ? dA2 : 0) + (size_t)(t + 2) * kstep; const char* b2 = last ? nB : cB + ((Epi::HAS_MID && t + 2 >= nt1) ? dB2 : 0) + (size_t)(t + 2) * kstep;
;     ...
; #pragma unroll
;         for (int a = 0; a < 2; ++a)
; #pragma unroll
;             for (int b = 0; b < 2; ++b)
; #pragma unroll
;                 for (int m = 0; m < 4; ++m)
; #pragma unroll
;                     for (int n = 0; n < 2; ++n) acc[a][b][m][n] = (f32x4){0.f, 0.f, 0.f, 0.f};
;         cur = nxt; cA = nA; cB = nB; ++ui;
.LBB0_719:
	s_ashr_i32 s47, s46, 31
	s_lshl_b64 s[6:7], s[46:47], 19
	s_add_u32 s52, s54, s6
	s_addc_u32 s53, s55, s7
	s_and_b64 s[6:7], s[8:9], exec
	s_cselect_b32 s6, s53, s63
	s_cselect_b32 s7, s52, s62
	s_ashr_i32 s15, s14, 31
	s_lshl_b64 s[36:37], s[14:15], 19
	s_add_u32 s56, s70, s36
	s_addc_u32 s57, s71, s37
	s_and_b64 s[36:37], s[8:9], exec
	s_cselect_b32 s15, s57, s65
	s_cselect_b32 s35, s56, s64
	s_add_u32 s62, s62, 0x40080
	s_addc_u32 s63, s63, 0
	s_add_u32 s36, s64, 0x100
	v_mov_b32_e32 v0, 0
	s_addc_u32 s37, s65, 0
	s_mov_b32 s38, -2
	v_mov_b32_e32 v1, v0
	v_mov_b32_e32 v2, v0
	v_mov_b32_e32 v3, v0
	v_mov_b32_e32 v4, v0
	v_mov_b32_e32 v5, v0
	v_mov_b32_e32 v6, v0
	v_mov_b32_e32 v7, v0
	v_mov_b32_e32 v16, v0
	v_mov_b32_e32 v17, v0
	v_mov_b32_e32 v18, v0
	v_mov_b32_e32 v19, v0
	v_mov_b32_e32 v20, v0
	v_mov_b32_e32 v21, v0
	v_mov_b32_e32 v22, v0
	v_mov_b32_e32 v23, v0
	v_mov_b32_e32 v32, v0
	v_mov_b32_e32 v33, v0
	v_mov_b32_e32 v34, v0
	v_mov_b32_e32 v35, v0
	v_mov_b32_e32 v36, v0
	v_mov_b32_e32 v37, v0
	v_mov_b32_e32 v38, v0
	v_mov_b32_e32 v39, v0
	v_mov_b32_e32 v48, v0
	v_mov_b32_e32 v49, v0
	v_mov_b32_e32 v50, v0
	v_mov_b32_e32 v51, v0
	v_mov_b32_e32 v52, v0
	v_mov_b32_e32 v53, v0
	v_mov_b32_e32 v54, v0
	v_mov_b32_e32 v55, v0
	v_mov_b32_e32 v8, v0
	v_mov_b32_e32 v9, v0
	v_mov_b32_e32 v10, v0
	v_mov_b32_e32 v11, v0
	v_mov_b32_e32 v12, v0
	v_mov_b32_e32 v13, v0
	v_mov_b32_e32 v14, v0
	v_mov_b32_e32 v15, v0
	v_mov_b32_e32 v24, v0
	v_mov_b32_e32 v25, v0
	v_mov_b32_e32 v26, v0
	v_mov_b32_e32 v27, v0
	v_mov_b32_e32 v28, v0
	v_mov_b32_e32 v29, v0
	v_mov_b32_e32 v30, v0
	v_mov_b32_e32 v31, v0
	v_mov_b32_e32 v40, v0
	v_mov_b32_e32 v41, v0
	v_mov_b32_e32 v42, v0
	v_mov_b32_e32 v43, v0
	v_mov_b32_e32 v44, v0
	v_mov_b32_e32 v45, v0
	v_mov_b32_e32 v46, v0
	v_mov_b32_e32 v47, v0
	v_mov_b32_e32 v56, v0
	v_mov_b32_e32 v57, v0
	v_mov_b32_e32 v58, v0
	v_mov_b32_e32 v59, v0
	v_mov_b32_e32 v60, v0
	v_mov_b32_e32 v61, v0
	v_mov_b32_e32 v62, v0
	v_mov_b32_e32 v63, v0
	v_mov_b32_e32 v64, v0
	v_mov_b32_e32 v65, v0
	v_mov_b32_e32 v66, v0
	v_mov_b32_e32 v67, v0
	v_mov_b32_e32 v68, v0
	v_mov_b32_e32 v69, v0
	v_mov_b32_e32 v70, v0
	v_mov_b32_e32 v71, v0
	v_mov_b32_e32 v80, v0
	v_mov_b32_e32 v81, v0
	v_mov_b32_e32 v82, v0
	v_mov_b32_e32 v83, v0
	v_mov_b32_e32 v84, v0
	v_mov_b32_e32 v85, v0
	v_mov_b32_e32 v86, v0
	v_mov_b32_e32 v87, v0
	v_mov_b32_e32 v96, v0
	v_mov_b32_e32 v97, v0
	v_mov_b32_e32 v98, v0
	v_mov_b32_e32 v99, v0
	v_mov_b32_e32 v100, v0
	v_mov_b32_e32 v101, v0
	v_mov_b32_e32 v102, v0
	v_mov_b32_e32 v103, v0
	v_mov_b32_e32 v112, v0
	v_mov_b32_e32 v113, v0
	v_mov_b32_e32 v114, v0
	v_mov_b32_e32 v115, v0
	v_mov_b32_e32 v116, v0
	v_mov_b32_e32 v117, v0
	v_mov_b32_e32 v118, v0
	v_mov_b32_e32 v119, v0
	v_mov_b32_e32 v72, v0
	v_mov_b32_e32 v73, v0
	v_mov_b32_e32 v74, v0
	v_mov_b32_e32 v75, v0
	v_mov_b32_e32 v76, v0
	v_mov_b32_e32 v77, v0
	v_mov_b32_e32 v78, v0
	v_mov_b32_e32 v79, v0
	v_mov_b32_e32 v88, v0
	v_mov_b32_e32 v89, v0
	v_mov_b32_e32 v90, v0
	v_mov_b32_e32 v91, v0
	v_mov_b32_e32 v92, v0
	v_mov_b32_e32 v93, v0
	v_mov_b32_e32 v94, v0
	v_mov_b32_e32 v95, v0
	v_mov_b32_e32 v104, v0
	v_mov_b32_e32 v105, v0
	v_mov_b32_e32 v106, v0
	v_mov_b32_e32 v107, v0
	v_mov_b32_e32 v108, v0
	v_mov_b32_e32 v109, v0
	v_mov_b32_e32 v110, v0
	v_mov_b32_e32 v111, v0
	v_mov_b32_e32 v120, v0
	v_mov_b32_e32 v121, v0
	v_mov_b32_e32 v122, v0
	v_mov_b32_e32 v123, v0
	v_mov_b32_e32 v124, v0
	v_mov_b32_e32 v125, v0
	v_mov_b32_e32 v126, v0
	v_mov_b32_e32 v127, v0
	.p2alignl 6, 3212836864

; #define DMA_T(s_) do { DMA_K(s_); DMA_V(s_); } while (0)
; #define WAIT_BAR() do { asm volatile("s_waitcnt vmcnt(0) lgkmcnt(0)" ::: "memory"); __builtin_amdgcn_s_barrier(); asm volatile("" ::: "memory"); } while (0)
; template <bool SWA>
; __device__ __forceinline__ void unit(LAS unsigned char* lds, const bf16_t* PROJ, const bf16_t* KT, const bf16_t* VT, bf16_t* OB, int opitch, int ocol, int b, int head, int qb, float slope2, float m_init, float lam, const float* subg) {
;     ...
;     for (int S = 0; S < npairs; ++S) {
;         const int sa = 2 * S, sb = 2 * S + 1;
;         if (sa + 2 < nsteps) DMA_T(sa + 2);
;     ...
;         WAIT_BAR();
.LBB0_883:
	s_waitcnt vmcnt(0) lgkmcnt(0)
	s_barrier
	s_add_i32 s1, s1, 2
	s_add_i32 s25, s25, 0x8000
	s_cmp_eq_u32 s1, 33
	s_cbranch_scc1 .LBB0_917
	.p2alignl 6, 3212836864

; #define WAIT_BAR() do { asm volatile("s_waitcnt vmcnt(0) lgkmcnt(0)" ::: "memory"); __builtin_amdgcn_s_barrier(); asm volatile("" ::: "memory"); } while (0)
; template <bool SWA>
; __device__ __forceinline__ void unit(LAS unsigned char* lds, const bf16_t* PROJ, const bf16_t* KT, const bf16_t* VT, bf16_t* OB, int opitch, int ocol, int b, int head, int qb, float slope2, float m_init, float lam, const float* subg) {
;     ...
;     f32x16 o[NDB];
; #pragma unroll
;     for (int db = 0; db < NDB; ++db)
; #pragma unroll
;         for (int i = 0; i < 16; ++i) o[db][i] = 0.f;
;     float mrun = m_init, lrun = (SWA && h == 0) ? 1.0f : 0.0f;
;     const int krow = (r & 0x13) | ((r & 4) << 1) | ((r & 8) >> 1);
;     int offK[4], offV[4];
; #pragma unroll
;     for (int ks = 0; ks < 4; ++ks) {
;         if (SWA) offK[ks] = krow * 128 + (((2 * ks + h) ^ ((krow >> 1) & 7)) << 4);
;         else offK[ks] = krow * 256 + (((c * 8 + 2 * ks + h) ^ (krow & 15)) << 4);
;         offV[ks] = r * 128 + (((2 * ks + h) ^ ((r >> 1) & 7)) << 4);
;     }
;     bf16x8 pf[4]; bool pvalid = false;
;     asm volatile("" : "+v"(qf[0]), "+v"(qf[1]), "+v"(qf[2]), "+v"(qf[3]));
;     WAIT_BAR();
;     const int npairs = (nsteps + 1) >> 1;
.Lsq_nopf:
	v_lshrrev_b32_e32 v6, 1, v143
	v_and_b32_e32 v5, 19, v143
	v_and_b32_e32 v4, 8, v4
	v_and_b32_e32 v7, 4, v6
	v_or3_b32 v4, v4, v5, v7
	v_lshlrev_b32_e32 v7, 7, v144
	v_bitop3_b32 v6, v2, v6, 7 bitop3:0x78
	v_lshlrev_b32_e32 v5, 7, v4
	v_lshrrev_b32_e32 v4, 1, v4
	v_lshl_or_b32 v149, v6, 4, v7
	v_or_b32_e32 v6, 2, v2
	v_bfe_u32 v8, v143, 1, 3
	v_bitop3_b32 v6, v4, v6, 7 bitop3:0x6c
	v_lshl_or_b32 v150, v6, 4, v5
	v_bitop3_b32 v6, v2, v8, 2 bitop3:0x36
	v_lshl_or_b32 v151, v6, 4, v7
	v_or_b32_e32 v6, 4, v2
	v_bitop3_b32 v6, v4, v6, 7 bitop3:0x6c
	v_lshl_or_b32 v152, v6, 4, v5
	v_bitop3_b32 v6, v2, v8, 4 bitop3:0x36
	v_lshl_or_b32 v153, v6, 4, v7
	v_or_b32_e32 v6, 6, v2
	s_add_i32 s0, s8, 1
	v_bitop3_b32 v9, v4, v2, 7 bitop3:0x6c
	v_bitop3_b32 v4, v4, v6, 7 bitop3:0x6c
	v_cvt_f32_i32_e32 v6, s0
	v_bitop3_b32 v2, v2, v8, 6 bitop3:0x36
	v_lshl_or_b32 v155, v2, 4, v7
	v_mul_f32_e32 v162, 0x3fb8aa3b, v3
	v_mul_f32_e32 v2, -0.5, v6
	v_cmp_gt_f32_e32 vcc, s4, v2
	s_and_b64 s[0:1], vcc, exec
	s_cselect_b32 s0, 0xffffffc0, 0
	v_cndmask_b32_e32 v2, 0, v140, vcc
	v_fmac_f32_e32 v2, -0.5, v6
	v_exp_f32_e32 v2, v2
	v_mov_b32_e32 v3, v1
	v_lshl_or_b32 v148, v9, 4, v5
	v_lshl_or_b32 v154, v4, 4, v5
	v_ldexp_f32 v2, v2, s0
	v_mul_f32_e32 v156, 0x3fb8aa3b, v2
	v_mov_b32_e32 v2, s16
	s_and_b32 s0, s16, 31
	v_and_b32_e32 v2, 31, v2
	s_lshl_b32 s8, s0, 6
	v_cmp_lt_u64_e32 vcc, 2, v[2:3]
	s_or_b32 s7, s8, s7
	s_addk_i32 s7, 0x80
	v_cndmask_b32_e32 v2, 2, v2, vcc
	v_lshlrev_b32_e32 v2, 13, v2
	s_max_u32 s0, s0, 2
	v_lshl_add_u64 v[4:5], s[10:11], 0, v[0:1]
	v_lshl_add_u64 v[6:7], s[78:79], 0, v[0:1]
	v_add_u32_e32 v0, s7, v144
	s_lshl_b32 s9, s0, 6
	s_and_b32 s0, s19, 0xffffff80
	v_lshl_add_u64 v[130:131], v[6:7], 0, v[2:3]
	v_lshl_add_u64 v[132:133], v[4:5], 0, v[2:3]
	v_sub_u32_e32 v0, v0, v146
	v_mov_b32_e32 v2, v1
	v_mov_b32_e32 v4, v1
	v_mov_b32_e32 v5, v1
	v_mov_b32_e32 v6, v1
	v_mov_b32_e32 v7, v1
	v_mov_b32_e32 v8, v1
	v_mov_b32_e32 v9, v1
	v_mov_b32_e32 v10, v1
	v_mov_b32_e32 v11, v1
	v_mov_b32_e32 v12, v1
	v_mov_b32_e32 v13, v1
	v_mov_b32_e32 v14, v1
	v_mov_b32_e32 v15, v1
	v_mov_b32_e32 v16, v1
	v_mov_b32_e32 v17, v1
	v_mov_b32_e32 v18, v1
	v_mov_b32_e32 v19, v1
	v_mov_b32_e32 v20, v1
	v_mov_b32_e32 v21, v1
	v_mov_b32_e32 v22, v1
	v_mov_b32_e32 v23, v1
	v_mov_b32_e32 v24, v1
	v_mov_b32_e32 v25, v1
	v_mov_b32_e32 v26, v1
	v_mov_b32_e32 v27, v1
	v_mov_b32_e32 v28, v1
	v_mov_b32_e32 v29, v1
	v_mov_b32_e32 v30, v1
	v_mov_b32_e32 v31, v1
	s_add_i32 s48, s0, 0
	v_readfirstlane_b32 s78, v156
	v_subrev_u32_e32 v159, s9, v0
	v_mov_b32_e32 v0, v1
	v_mov_b64_e32 v[32:33], v[30:31]
	s_mov_b32 s6, 0
	s_add_i32 s29, s29, -2
	s_add_i32 s30, s9, 0xffffff80
	s_add_i32 s31, s25, 0xffffff80
	s_add_i32 s33, s25, 0x9f
	s_or_b32 s40, s25, 31
	s_add_i32 s41, s25, 0xffffff9e
	s_add_i32 s48, s48, 0x20200
	v_mul_f32_e32 v157, 0x42000000, v156
	s_add_i32 s49, s25, 0x41
	v_or_b32_e32 v158, s25, v144
	s_mov_b32 s79, s78
	s_mov_b32 s50, s78
	s_mov_b32 s51, s78
	s_mov_b32 s72, s78
	s_mov_b32 s73, s78
	s_mov_b32 s94, s78
	s_mov_b32 s95, s78
	s_mov_b32 s96, s78
	s_mov_b32 s97, s78
	s_mov_b32 s2, s78
	s_mov_b32 s3, s78
	s_mov_b32 s13, s78
	s_mov_b32 s0, s78
	s_mov_b32 s1, s78
	s_mov_b32 s34, s78
	s_mov_b64 s[80:81], 0
	v_mov_b64_e32 v[30:31], v[28:29]
	v_mov_b64_e32 v[28:29], v[26:27]
	v_mov_b64_e32 v[26:27], v[24:25]
	v_mov_b64_e32 v[24:25], v[22:23]
	v_mov_b64_e32 v[22:23], v[20:21]
	v_mov_b64_e32 v[20:21], v[18:19]
	v_mov_b64_e32 v[18:19], v[16:17]
	v_mov_b64_e32 v[16:17], v[14:15]
	v_mov_b64_e32 v[14:15], v[12:13]
	v_mov_b64_e32 v[12:13], v[10:11]
	v_mov_b64_e32 v[10:11], v[8:9]
	v_mov_b64_e32 v[8:9], v[6:7]
	v_mov_b64_e32 v[6:7], v[4:5]
	v_mov_b64_e32 v[4:5], v[2:3]
	v_mov_b64_e32 v[2:3], v[0:1]
	.p2alignl 6, 3212836864

; #define PG8_STAGE(bufoff, gbase, voff) do { _Pragma("unroll") for (int _i = 0; _i < 2; ++_i) \
;         __builtin_amdgcn_global_load_lds((const unsigned*)((const char*)(gbase) + (voff)[_i]), (LAS unsigned*)(lds + (bufoff) + ldsw + _i * 8192), 16, 0, 0); } while (0)
; #define PG8_LDA(dst, b, h) do { _Pragma("unroll") for (int m = 0; m < 4; ++m) _Pragma("unroll") for (int k = 0; k < 2; ++k) dst[m][k] = *(const LAS bf16x8*)(lds + PG8_SA(b, h) + aoff + m * 2048 + k * 1024); } while (0)
; #define PG8_LDB(dst, b, h) do { _Pragma("unroll") for (int n = 0; n < 2; ++n) _Pragma("unroll") for (int k = 0; k < 2; ++k) dst[n][k] = *(const LAS bf16x8*)(lds + PG8_SB(b, h) + boff + n * 2048 + k * 1024); } while (0)
; #define PG8_MMA(ai, bj, At, Bt) do { __builtin_amdgcn_s_setprio(1); _Pragma("unroll") for (int m = 0; m < 4; ++m) _Pragma("unroll") for (int n = 0; n < 2; ++n) _Pragma("unroll") for (int k = 0; k < 2; ++k) \
;         acc[ai][bj][m][n] = __builtin_amdgcn_mfma_f32_16x16x32_bf16(Bt[n][k], At[m][k], acc[ai][bj][m][n], 0, 0, 0); __builtin_amdgcn_s_setprio(0); } while (0)
; #define PG8_WAIT_V(n) asm volatile("s_waitcnt vmcnt(" #n ")" ::: "memory")
; template <class Epi>
; __device__ __forceinline__ void gemm_phase(LAS unsigned char* lds, const Gemm g, const StaticOrder& S, const Epi& E) {
;     ...
;         for (int t = 0; t < nt; t += 2) {
;             const bool last = (t == nt - 2);
;             if constexpr (Epi::HAS_MID) { if (t == nt1) E.mid(acc, cur, wr, wc, fr, fq); }
;             const char* a1 = cA + ((Epi::HAS_MID && t >= nt1) ? dA2 : 0) + (size_t)(t + 1) * kstep;
;             const char* a2 = last ? nA : cA + ((Epi::HAS_MID && t + 2 >= nt1) ? dA2 : 0) + (size_t)(t + 2) * kstep; const char* b2 = last ? nB : cB + ((Epi::HAS_MID && t + 2 >= nt1) ? dB2 : 0) + (size_t)(t + 2) * kstep;
;             const char* a3 = a2 + kstep; const char* b3 = b2 + kstep;
;             PG8_LDB(B0, 0, 0); PG8_LDB(B1, 0, 1); PG8_SCHED; PG8_LDA(At, 0, 0); PG8_STAGE(PG8_SA(1, 1), a1 + hsA, voffA);
;             PG8_WAIT_V(8); PG8_WAIT_L(0); PG8_BAR; PG8_MMA(0, 0, At, B0); PG8_MMA(0, 1, At, B1); PG8_BAR; PG8_SCHED;
;             PG8_LDA(At, 0, 1); PG8_STAGE(PG8_SB(0, 0), b2, voffB); PG8_STAGE(PG8_SB(0, 1), b2 + hsB, voffB); PG8_STAGE(PG8_SA(0, 0), a2, voffA);
;             PG8_WAIT_V(8); PG8_WAIT_L(0); PG8_BAR; PG8_MMA(1, 0, At, B0); PG8_MMA(1, 1, At, B1); PG8_BAR; PG8_SCHED;
.LBB0_1083:
	s_add_i32 s33, s33, 2
	s_add_u32 s0, s52, s54
	s_addc_u32 s1, s53, s55
	s_add_u32 s0, s0, 0x100
	v_add_u32_e32 v153, s74, v171
	s_addc_u32 s1, s1, 0
	ds_read_b128 v[128:131], v153
	ds_read_b128 v[132:135], v153 offset:1024
	ds_read_b128 v[164:167], v153 offset:2048
	ds_read_b128 v[184:187], v153 offset:3072
	v_add_u32_e32 v153, s75, v171
	s_cmp_gt_u32 s33, 13
	ds_read_b128 v[188:191], v153
	ds_read_b128 v[192:195], v153 offset:1024
	ds_read_b128 v[196:199], v153 offset:2048
	ds_read_b128 v[200:203], v153 offset:3072
	s_cselect_b32 s17, 0x1ff800, 0
	s_add_u32 s17, s17, s54
	s_addc_u32 s24, 0, s55
	s_add_u32 s17, s22, s17
	s_addc_u32 s24, s23, s24
	s_cmpk_eq_i32 s54, 0xf00
	s_cselect_b32 s59, s6, s1
	s_cselect_b32 s58, s7, s0
	s_cselect_b32 s57, s16, s24
	s_cselect_b32 s56, s18, s17
	v_lshl_add_u64 v[168:169], v[158:159], 0, s[54:55]
	s_add_i32 m0, s61, 0xc000
	ds_read_b128 v[204:207], v173
	ds_read_b128 v[208:211], v173 offset:1024
	ds_read_b128 v[212:215], v173 offset:2048
	ds_read_b128 v[216:219], v173 offset:3072
	ds_read_b128 v[220:223], v173 offset:4096
	ds_read_b128 v[224:227], v173 offset:5120
	ds_read_b128 v[228:231], v173 offset:6144
	ds_read_b128 v[232:235], v173 offset:7168
	global_load_lds_dwordx4 v[168:169], off
	v_lshl_add_u64 v[168:169], v[162:163], 0, s[54:55]
	s_add_i32 m0, s61, 0xe000
	s_nop 0
	global_load_lds_dwordx4 v[168:169], off
	s_waitcnt vmcnt(8)
	s_waitcnt lgkmcnt(0)
	s_barrier
	s_setprio 1
	s_waitcnt lgkmcnt(0)
	v_mfma_f32_16x16x32_bf16 v[124:127], v[128:131], v[204:207], v[124:127]
	v_mfma_f32_16x16x32_bf16 v[120:123], v[164:167], v[204:207], v[120:123]
	v_mfma_f32_16x16x32_bf16 v[108:111], v[128:131], v[212:215], v[108:111]
	v_mfma_f32_16x16x32_bf16 v[104:107], v[164:167], v[212:215], v[104:107]
	v_mfma_f32_16x16x32_bf16 v[92:95], v[128:131], v[220:223], v[92:95]
	v_mfma_f32_16x16x32_bf16 v[88:91], v[164:167], v[220:223], v[88:91]
	v_mfma_f32_16x16x32_bf16 v[76:79], v[128:131], v[228:231], v[76:79]
	v_mfma_f32_16x16x32_bf16 v[72:75], v[164:167], v[228:231], v[72:75]
	v_mfma_f32_16x16x32_bf16 v[124:127], v[132:135], v[208:211], v[124:127]
	v_mfma_f32_16x16x32_bf16 v[120:123], v[184:187], v[208:211], v[120:123]
	v_mfma_f32_16x16x32_bf16 v[108:111], v[132:135], v[216:219], v[108:111]
	v_mfma_f32_16x16x32_bf16 v[104:107], v[184:187], v[216:219], v[104:107]
	v_mfma_f32_16x16x32_bf16 v[92:95], v[132:135], v[224:227], v[92:95]
	v_mfma_f32_16x16x32_bf16 v[88:91], v[184:187], v[224:227], v[88:91]
	v_mfma_f32_16x16x32_bf16 v[76:79], v[132:135], v[232:235], v[76:79]
	v_mfma_f32_16x16x32_bf16 v[72:75], v[184:187], v[232:235], v[72:75]
	s_setprio 0
	s_setprio 1
	v_mfma_f32_16x16x32_bf16 v[116:119], v[188:191], v[204:207], v[116:119]
	v_mfma_f32_16x16x32_bf16 v[112:115], v[196:199], v[204:207], v[112:115]
	v_mfma_f32_16x16x32_bf16 v[100:103], v[188:191], v[212:215], v[100:103]
	v_mfma_f32_16x16x32_bf16 v[96:99], v[196:199], v[212:215], v[96:99]
	v_mfma_f32_16x16x32_bf16 v[84:87], v[188:191], v[220:223], v[84:87]
	v_mfma_f32_16x16x32_bf16 v[80:83], v[196:199], v[220:223], v[80:83]
	v_mfma_f32_16x16x32_bf16 v[68:71], v[188:191], v[228:231], v[68:71]
	v_mfma_f32_16x16x32_bf16 v[64:67], v[196:199], v[228:231], v[64:67]
	v_mfma_f32_16x16x32_bf16 v[116:119], v[192:195], v[208:211], v[116:119]
	v_mfma_f32_16x16x32_bf16 v[112:115], v[200:203], v[208:211], v[112:115]
	v_mfma_f32_16x16x32_bf16 v[100:103], v[192:195], v[216:219], v[100:103]
	v_mfma_f32_16x16x32_bf16 v[96:99], v[200:203], v[216:219], v[96:99]
	v_mfma_f32_16x16x32_bf16 v[84:87], v[192:195], v[224:227], v[84:87]
	v_mfma_f32_16x16x32_bf16 v[80:83], v[200:203], v[224:227], v[80:83]
	v_mfma_f32_16x16x32_bf16 v[68:71], v[192:195], v[232:235], v[68:71]
	v_mfma_f32_16x16x32_bf16 v[64:67], v[200:203], v[232:235], v[64:67]
	s_setprio 0
	s_barrier
	s_add_i32 s0, s74, s60
	v_lshl_add_u64 v[168:169], s[56:57], 0, v[138:139]
	s_mov_b32 m0, s0
	ds_read_b128 v[204:207], v173 offset:16384
	ds_read_b128 v[208:211], v173 offset:17408
	ds_read_b128 v[212:215], v173 offset:18432
	ds_read_b128 v[216:219], v173 offset:19456
	ds_read_b128 v[220:223], v173 offset:20480
	ds_read_b128 v[224:227], v173 offset:21504
	ds_read_b128 v[228:231], v173 offset:22528
	ds_read_b128 v[232:235], v173 offset:23552
	global_load_lds_dwordx4 v[168:169], off
	s_add_i32 m0, s0, 0x2000
	s_add_u32 s0, s56, 0x40000
	v_lshl_add_u64 v[236:237], s[56:57], 0, v[142:143]
	s_addc_u32 s1, s57, 0
	s_add_i32 s17, s75, s60
	global_load_lds_dwordx4 v[236:237], off
	v_lshl_add_u64 v[238:239], s[0:1], 0, v[138:139]
	s_mov_b32 m0, s17
	v_lshl_add_u64 v[240:241], s[58:59], 0, v[140:141]
	global_load_lds_dwordx4 v[238:239], off
	v_lshl_add_u64 v[238:239], s[0:1], 0, v[142:143]
	s_add_i32 m0, s17, 0x2000
	s_nop 0
	global_load_lds_dwordx4 v[238:239], off
	v_lshl_add_u64 v[238:239], s[58:59], 0, v[136:137]
	s_mov_b32 m0, s61
	s_nop 0
	global_load_lds_dwordx4 v[238:239], off
	s_mov_b32 m0, s4
	s_nop 0
	global_load_lds_dwordx4 v[240:241], off
	s_waitcnt vmcnt(8)
	s_waitcnt lgkmcnt(0)
	s_barrier
; #define PG8_STAGE(bufoff, gbase, voff) do { _Pragma("unroll") for (int _i = 0; _i < 2; ++_i) \
;         __builtin_amdgcn_global_load_lds((const unsigned*)((const char*)(gbase) + (voff)[_i]), (LAS unsigned*)(lds + (bufoff) + ldsw + _i * 8192), 16, 0, 0); } while (0)
; #define PG8_LDA(dst, b, h) do { _Pragma("unroll") for (int m = 0; m < 4; ++m) _Pragma("unroll") for (int k = 0; k < 2; ++k) dst[m][k] = *(const LAS bf16x8*)(lds + PG8_SA(b, h) + aoff + m * 2048 + k * 1024); } while (0)
; #define PG8_LDB(dst, b, h) do { _Pragma("unroll") for (int n = 0; n < 2; ++n) _Pragma("unroll") for (int k = 0; k < 2; ++k) dst[n][k] = *(const LAS bf16x8*)(lds + PG8_SB(b, h) + boff + n * 2048 + k * 1024); } while (0)
; #define PG8_MMA(ai, bj, At, Bt) do { __builtin_amdgcn_s_setprio(1); _Pragma("unroll") for (int m = 0; m < 4; ++m) _Pragma("unroll") for (int n = 0; n < 2; ++n) _Pragma("unroll") for (int k = 0; k < 2; ++k) \
;         acc[ai][bj][m][n] = __builtin_amdgcn_mfma_f32_16x16x32_bf16(Bt[n][k], At[m][k], acc[ai][bj][m][n], 0, 0, 0); __builtin_amdgcn_s_setprio(0); } while (0)
; #define PG8_WAIT_V(n) asm volatile("s_waitcnt vmcnt(" #n ")" ::: "memory")
; #define PG8_WAIT_L(n) asm volatile("s_waitcnt lgkmcnt(" #n ")" ::: "memory")
; #define PG8_BAR __builtin_amdgcn_s_barrier()
; #define PG8_SCHED __builtin_amdgcn_sched_barrier(0)
; template <class Epi>
; __device__ __forceinline__ void gemm_phase(LAS unsigned char* lds, const Gemm g, const StaticOrder& S, const Epi& E) {
;     ...
;             PG8_WAIT_V(8); PG8_WAIT_L(0); PG8_BAR; PG8_MMA(1, 0, At, B0); PG8_MMA(1, 1, At, B1); PG8_BAR; PG8_SCHED;
;             PG8_LDB(B0, 1, 0); PG8_LDB(B1, 1, 1); PG8_SCHED; PG8_LDA(At, 1, 0); PG8_STAGE(PG8_SA(0, 1), a2 + hsA, voffA);
;             PG8_WAIT_V(8); PG8_WAIT_L(0); PG8_BAR; PG8_MMA(0, 0, At, B0); PG8_MMA(0, 1, At, B1); PG8_BAR; PG8_SCHED;
;             PG8_LDA(At, 1, 1); PG8_STAGE(PG8_SB(1, 0), b3, voffB); PG8_STAGE(PG8_SB(1, 1), b3 + hsB, voffB); PG8_STAGE(PG8_SA(1, 0), a3, voffA);
	s_setprio 1
	s_waitcnt lgkmcnt(0)
	v_mfma_f32_16x16x32_bf16 v[60:63], v[128:131], v[204:207], v[60:63]
	v_mfma_f32_16x16x32_bf16 v[56:59], v[164:167], v[204:207], v[56:59]
	v_mfma_f32_16x16x32_bf16 v[44:47], v[128:131], v[212:215], v[44:47]
	v_mfma_f32_16x16x32_bf16 v[40:43], v[164:167], v[212:215], v[40:43]
	v_mfma_f32_16x16x32_bf16 v[28:31], v[128:131], v[220:223], v[28:31]
	v_mfma_f32_16x16x32_bf16 v[24:27], v[164:167], v[220:223], v[24:27]
	v_mfma_f32_16x16x32_bf16 v[12:15], v[128:131], v[228:231], v[12:15]
	v_mfma_f32_16x16x32_bf16 v[8:11], v[164:167], v[228:231], v[8:11]
	v_mfma_f32_16x16x32_bf16 v[60:63], v[132:135], v[208:211], v[60:63]
	v_mfma_f32_16x16x32_bf16 v[56:59], v[184:187], v[208:211], v[56:59]
	v_mfma_f32_16x16x32_bf16 v[44:47], v[132:135], v[216:219], v[44:47]
	v_mfma_f32_16x16x32_bf16 v[40:43], v[184:187], v[216:219], v[40:43]
	v_mfma_f32_16x16x32_bf16 v[28:31], v[132:135], v[224:227], v[28:31]
	v_mfma_f32_16x16x32_bf16 v[24:27], v[184:187], v[224:227], v[24:27]
	v_mfma_f32_16x16x32_bf16 v[12:15], v[132:135], v[232:235], v[12:15]
	v_mfma_f32_16x16x32_bf16 v[8:11], v[184:187], v[232:235], v[8:11]
	s_setprio 0
	s_setprio 1
	v_mfma_f32_16x16x32_bf16 v[52:55], v[188:191], v[204:207], v[52:55]
	v_mfma_f32_16x16x32_bf16 v[48:51], v[196:199], v[204:207], v[48:51]
	v_mfma_f32_16x16x32_bf16 v[36:39], v[188:191], v[212:215], v[36:39]
	v_mfma_f32_16x16x32_bf16 v[32:35], v[196:199], v[212:215], v[32:35]
	v_mfma_f32_16x16x32_bf16 v[20:23], v[188:191], v[220:223], v[20:23]
	v_mfma_f32_16x16x32_bf16 v[16:19], v[196:199], v[220:223], v[16:19]
	v_mfma_f32_16x16x32_bf16 v[4:7], v[188:191], v[228:231], v[4:7]
	v_mfma_f32_16x16x32_bf16 v[0:3], v[196:199], v[228:231], v[0:3]
	v_mfma_f32_16x16x32_bf16 v[52:55], v[192:195], v[208:211], v[52:55]
	v_mfma_f32_16x16x32_bf16 v[48:51], v[200:203], v[208:211], v[48:51]
	v_mfma_f32_16x16x32_bf16 v[36:39], v[192:195], v[216:219], v[36:39]
	v_mfma_f32_16x16x32_bf16 v[32:35], v[200:203], v[216:219], v[32:35]
	v_mfma_f32_16x16x32_bf16 v[20:23], v[192:195], v[224:227], v[20:23]
	v_mfma_f32_16x16x32_bf16 v[16:19], v[200:203], v[224:227], v[16:19]
	v_mfma_f32_16x16x32_bf16 v[4:7], v[192:195], v[232:235], v[4:7]
	v_mfma_f32_16x16x32_bf16 v[0:3], v[200:203], v[232:235], v[0:3]
	s_setprio 0
	s_barrier
	s_add_i32 s17, 0, 0x18000
	v_add_u32_e32 v153, s17, v171
	s_add_i32 s24, 0, 0x1c000
	ds_read_b128 v[128:131], v153
	ds_read_b128 v[132:135], v153 offset:1024
	ds_read_b128 v[164:167], v153 offset:2048
	ds_read_b128 v[184:187], v153 offset:3072
	v_add_u32_e32 v153, s24, v171
	ds_read_b128 v[188:191], v153
	ds_read_b128 v[192:195], v153 offset:1024
	ds_read_b128 v[196:199], v153 offset:2048
	ds_read_b128 v[200:203], v153 offset:3072
	s_add_u32 s0, s58, 0x100000
	s_addc_u32 s1, s59, 0
	s_mov_b32 m0, s5
	v_lshl_add_u64 v[242:243], s[0:1], 0, v[136:137]
	ds_read_b128 v[204:207], v173 offset:32768
	ds_read_b128 v[208:211], v173 offset:33792
	ds_read_b128 v[212:215], v173 offset:34816
	ds_read_b128 v[216:219], v173 offset:35840
	ds_read_b128 v[220:223], v173 offset:36864
	ds_read_b128 v[224:227], v173 offset:37888
	ds_read_b128 v[228:231], v173 offset:38912
	ds_read_b128 v[232:235], v173 offset:39936
	global_load_lds_dwordx4 v[242:243], off
	v_lshl_add_u64 v[242:243], s[0:1], 0, v[140:141]
	s_mov_b32 m0, s62
	s_nop 0
	global_load_lds_dwordx4 v[242:243], off
	s_waitcnt vmcnt(8)
	s_waitcnt lgkmcnt(0)
	s_barrier
	s_setprio 1
	s_waitcnt lgkmcnt(0)
	v_mfma_f32_16x16x32_bf16 v[124:127], v[128:131], v[204:207], v[124:127]
	v_mfma_f32_16x16x32_bf16 v[120:123], v[164:167], v[204:207], v[120:123]
	v_mfma_f32_16x16x32_bf16 v[108:111], v[128:131], v[212:215], v[108:111]
	v_mfma_f32_16x16x32_bf16 v[104:107], v[164:167], v[212:215], v[104:107]
	v_mfma_f32_16x16x32_bf16 v[92:95], v[128:131], v[220:223], v[92:95]
	v_mfma_f32_16x16x32_bf16 v[88:91], v[164:167], v[220:223], v[88:91]
	v_mfma_f32_16x16x32_bf16 v[76:79], v[128:131], v[228:231], v[76:79]
	v_mfma_f32_16x16x32_bf16 v[72:75], v[164:167], v[228:231], v[72:75]
	v_mfma_f32_16x16x32_bf16 v[124:127], v[132:135], v[208:211], v[124:127]
	v_mfma_f32_16x16x32_bf16 v[120:123], v[184:187], v[208:211], v[120:123]
	v_mfma_f32_16x16x32_bf16 v[108:111], v[132:135], v[216:219], v[108:111]
	v_mfma_f32_16x16x32_bf16 v[104:107], v[184:187], v[216:219], v[104:107]
	v_mfma_f32_16x16x32_bf16 v[92:95], v[132:135], v[224:227], v[92:95]
	v_mfma_f32_16x16x32_bf16 v[88:91], v[184:187], v[224:227], v[88:91]
	v_mfma_f32_16x16x32_bf16 v[76:79], v[132:135], v[232:235], v[76:79]
	v_mfma_f32_16x16x32_bf16 v[72:75], v[184:187], v[232:235], v[72:75]
	s_setprio 0
	s_setprio 1
	v_mfma_f32_16x16x32_bf16 v[116:119], v[188:191], v[204:207], v[116:119]
	v_mfma_f32_16x16x32_bf16 v[112:115], v[196:199], v[204:207], v[112:115]
	v_mfma_f32_16x16x32_bf16 v[100:103], v[188:191], v[212:215], v[100:103]
	v_mfma_f32_16x16x32_bf16 v[96:99], v[196:199], v[212:215], v[96:99]
	v_mfma_f32_16x16x32_bf16 v[84:87], v[188:191], v[220:223], v[84:87]
	v_mfma_f32_16x16x32_bf16 v[80:83], v[196:199], v[220:223], v[80:83]
	v_mfma_f32_16x16x32_bf16 v[68:71], v[188:191], v[228:231], v[68:71]
	v_mfma_f32_16x16x32_bf16 v[64:67], v[196:199], v[228:231], v[64:67]
	v_mfma_f32_16x16x32_bf16 v[116:119], v[192:195], v[208:211], v[116:119]
	v_mfma_f32_16x16x32_bf16 v[112:115], v[200:203], v[208:211], v[112:115]
	v_mfma_f32_16x16x32_bf16 v[100:103], v[192:195], v[216:219], v[100:103]
	v_mfma_f32_16x16x32_bf16 v[96:99], v[200:203], v[216:219], v[96:99]
	v_mfma_f32_16x16x32_bf16 v[84:87], v[192:195], v[224:227], v[84:87]
	v_mfma_f32_16x16x32_bf16 v[80:83], v[200:203], v[224:227], v[80:83]
	v_mfma_f32_16x16x32_bf16 v[68:71], v[192:195], v[232:235], v[68:71]
	v_mfma_f32_16x16x32_bf16 v[64:67], v[200:203], v[232:235], v[64:67]
	s_setprio 0
	s_barrier
; #define PG8_STAGE(bufoff, gbase, voff) do { _Pragma("unroll") for (int _i = 0; _i < 2; ++_i) \
;         __builtin_amdgcn_global_load_lds((const unsigned*)((const char*)(gbase) + (voff)[_i]), (LAS unsigned*)(lds + (bufoff) + ldsw + _i * 8192), 16, 0, 0); } while (0)
; #define PG8_LDA(dst, b, h) do { _Pragma("unroll") for (int m = 0; m < 4; ++m) _Pragma("unroll") for (int k = 0; k < 2; ++k) dst[m][k] = *(const LAS bf16x8*)(lds + PG8_SA(b, h) + aoff + m * 2048 + k * 1024); } while (0)
; #define PG8_MMA(ai, bj, At, Bt) do { __builtin_amdgcn_s_setprio(1); _Pragma("unroll") for (int m = 0; m < 4; ++m) _Pragma("unroll") for (int n = 0; n < 2; ++n) _Pragma("unroll") for (int k = 0; k < 2; ++k) \
;         acc[ai][bj][m][n] = __builtin_amdgcn_mfma_f32_16x16x32_bf16(Bt[n][k], At[m][k], acc[ai][bj][m][n], 0, 0, 0); __builtin_amdgcn_s_setprio(0); } while (0)
; #define PG8_WAIT_V(n) asm volatile("s_waitcnt vmcnt(" #n ")" ::: "memory")
; #define PG8_WAIT_L(n) asm volatile("s_waitcnt lgkmcnt(" #n ")" ::: "memory")
; #define PG8_BAR __builtin_amdgcn_s_barrier()
; #define PG8_SCHED __builtin_amdgcn_sched_barrier(0)
; template <class Epi>
; __device__ __forceinline__ void gemm_phase(LAS unsigned char* lds, const Gemm g, const StaticOrder& S, const Epi& E) {
;     ...
;             PG8_LDA(At, 1, 1); PG8_STAGE(PG8_SB(1, 0), b3, voffB); PG8_STAGE(PG8_SB(1, 1), b3 + hsB, voffB); PG8_STAGE(PG8_SA(1, 0), a3, voffA);
;             PG8_WAIT_V(8); PG8_WAIT_L(0); PG8_BAR; PG8_MMA(1, 0, At, B0); PG8_MMA(1, 1, At, B1); PG8_BAR; PG8_SCHED;
;         }
	s_add_i32 s0, s17, s60
	v_lshl_add_u64 v[168:169], v[168:169], 0, s[10:11]
	s_mov_b32 m0, s0
	ds_read_b128 v[204:207], v173 offset:49152
	ds_read_b128 v[208:211], v173 offset:50176
	ds_read_b128 v[212:215], v173 offset:51200
	ds_read_b128 v[216:219], v173 offset:52224
	ds_read_b128 v[220:223], v173 offset:53248
	ds_read_b128 v[224:227], v173 offset:54272
	ds_read_b128 v[228:231], v173 offset:55296
	ds_read_b128 v[232:235], v173 offset:56320
	global_load_lds_dwordx4 v[168:169], off
	s_add_i32 m0, s0, 0x2000
	s_add_u32 s0, s56, 0x40080
	v_lshl_add_u64 v[168:169], v[236:237], 0, s[10:11]
	s_addc_u32 s1, s57, 0
	s_add_i32 s17, s24, s60
	global_load_lds_dwordx4 v[168:169], off
	v_lshl_add_u64 v[168:169], s[0:1], 0, v[138:139]
	s_mov_b32 m0, s17
	s_nop 0
	global_load_lds_dwordx4 v[168:169], off
	v_lshl_add_u64 v[168:169], s[0:1], 0, v[142:143]
	s_add_i32 m0, s17, 0x2000
	s_nop 0
	global_load_lds_dwordx4 v[168:169], off
	v_lshl_add_u64 v[168:169], v[238:239], 0, s[10:11]
	s_mov_b32 m0, s64
	s_nop 0
	global_load_lds_dwordx4 v[168:169], off
	v_lshl_add_u64 v[168:169], v[240:241], 0, s[10:11]
	s_mov_b32 m0, s65
	s_nop 0
	global_load_lds_dwordx4 v[168:169], off
	s_waitcnt vmcnt(8)
	s_waitcnt lgkmcnt(0)
	s_barrier
	s_setprio 1
	s_waitcnt lgkmcnt(0)
	v_mfma_f32_16x16x32_bf16 v[60:63], v[128:131], v[204:207], v[60:63]
	v_mfma_f32_16x16x32_bf16 v[56:59], v[164:167], v[204:207], v[56:59]
	v_mfma_f32_16x16x32_bf16 v[44:47], v[128:131], v[212:215], v[44:47]
	v_mfma_f32_16x16x32_bf16 v[40:43], v[164:167], v[212:215], v[40:43]
	v_mfma_f32_16x16x32_bf16 v[28:31], v[128:131], v[220:223], v[28:31]
	v_mfma_f32_16x16x32_bf16 v[24:27], v[164:167], v[220:223], v[24:27]
	v_mfma_f32_16x16x32_bf16 v[12:15], v[128:131], v[228:231], v[12:15]
	v_mfma_f32_16x16x32_bf16 v[8:11], v[164:167], v[228:231], v[8:11]
	v_mfma_f32_16x16x32_bf16 v[60:63], v[132:135], v[208:211], v[60:63]
	v_mfma_f32_16x16x32_bf16 v[56:59], v[184:187], v[208:211], v[56:59]
	v_mfma_f32_16x16x32_bf16 v[44:47], v[132:135], v[216:219], v[44:47]
	v_mfma_f32_16x16x32_bf16 v[40:43], v[184:187], v[216:219], v[40:43]
	v_mfma_f32_16x16x32_bf16 v[28:31], v[132:135], v[224:227], v[28:31]
	v_mfma_f32_16x16x32_bf16 v[24:27], v[184:187], v[224:227], v[24:27]
	v_mfma_f32_16x16x32_bf16 v[12:15], v[132:135], v[232:235], v[12:15]
	v_mfma_f32_16x16x32_bf16 v[8:11], v[184:187], v[232:235], v[8:11]
	s_setprio 0
	s_setprio 1
	v_mfma_f32_16x16x32_bf16 v[52:55], v[188:191], v[204:207], v[52:55]
	v_mfma_f32_16x16x32_bf16 v[48:51], v[196:199], v[204:207], v[48:51]
	v_mfma_f32_16x16x32_bf16 v[36:39], v[188:191], v[212:215], v[36:39]
	v_mfma_f32_16x16x32_bf16 v[32:35], v[196:199], v[212:215], v[32:35]
	v_mfma_f32_16x16x32_bf16 v[20:23], v[188:191], v[220:223], v[20:23]
	v_mfma_f32_16x16x32_bf16 v[16:19], v[196:199], v[220:223], v[16:19]
	v_mfma_f32_16x16x32_bf16 v[4:7], v[188:191], v[228:231], v[4:7]
	v_mfma_f32_16x16x32_bf16 v[0:3], v[196:199], v[228:231], v[0:3]
	v_mfma_f32_16x16x32_bf16 v[52:55], v[192:195], v[208:211], v[52:55]
	v_mfma_f32_16x16x32_bf16 v[48:51], v[200:203], v[208:211], v[48:51]
	v_mfma_f32_16x16x32_bf16 v[36:39], v[192:195], v[216:219], v[36:39]
	v_mfma_f32_16x16x32_bf16 v[32:35], v[200:203], v[216:219], v[32:35]
	v_mfma_f32_16x16x32_bf16 v[20:23], v[192:195], v[224:227], v[20:23]
	v_mfma_f32_16x16x32_bf16 v[16:19], v[200:203], v[224:227], v[16:19]
	v_mfma_f32_16x16x32_bf16 v[4:7], v[192:195], v[232:235], v[4:7]
	v_mfma_f32_16x16x32_bf16 v[0:3], v[200:203], v[232:235], v[0:3]
	s_setprio 0
	s_barrier
	s_add_u32 s54, s54, 0x100
	s_addc_u32 s55, 0, s55
	s_cmp_gt_u32 s33, 29
	s_cbranch_scc1 .LBB0_1086
	.p2alignl 6, 3212836864

; template <class Epi>
; __device__ __forceinline__ void gemm_phase(LAS unsigned char* lds, const Gemm g, const StaticOrder& S, const Epi& E) {
;     ...
;         const bool has_next = S.next(ui + 1, nxt);
;         const char* nA = has_next ? (const char*)g.A + (size_t)nxt.pm * tsA : cA; const char* nB = has_next ? (const char*)g.Bt + (size_t)nxt.pn * tsB : cB;
;         for (int t = 0; t < nt; t += 2) {
;             const bool last = (t == nt - 2);
;             if constexpr (Epi::HAS_MID) { if (t == nt1) E.mid(acc, cur, wr, wc, fr, fq); }
;             const char* a1 = cA + ((Epi::HAS_MID && t >= nt1) ? dA2 : 0) + (size_t)(t + 1) * kstep;
;             const char* a2 = last ? nA : cA + ((Epi::HAS_MID && t + 2 >= nt1) ? dA2 : 0) + (size_t)(t + 2) * kstep; const char* b2 = last ? nB : cB + ((Epi::HAS_MID && t + 2 >= nt1) ? dB2 : 0) + (size_t)(t + 2) * kstep;
;     ...
; #pragma unroll
;         for (int a = 0; a < 2; ++a)
; #pragma unroll
;             for (int b = 0; b < 2; ++b)
; #pragma unroll
;                 for (int m = 0; m < 4; ++m)
; #pragma unroll
;                     for (int n = 0; n < 2; ++n) acc[a][b][m][n] = (f32x4){0.f, 0.f, 0.f, 0.f};
;         cur = nxt; cA = nA; cB = nB; ++ui;
.LBB0_1233:
	s_ashr_i32 s41, s40, 31
	s_lshl_b64 s[0:1], s[40:41], 19
	s_add_u32 s42, s70, s0
	s_addc_u32 s43, s71, s1
	s_and_b64 s[0:1], s[10:11], exec
	s_cselect_b32 s0, s43, s49
	s_cselect_b32 s1, s42, s48
	s_ashr_i32 s39, s38, 31
	s_lshl_b64 s[6:7], s[38:39], 19
	s_add_u32 s44, s57, s6
	s_addc_u32 s45, s58, s7
	s_and_b64 s[6:7], s[10:11], exec
	s_cselect_b32 s6, s45, s51
	s_cselect_b32 s7, s44, s50
	s_add_u32 s48, s48, 0x40080
	s_addc_u32 s49, s49, 0
	s_add_u32 s13, s50, 0x100
	v_mov_b32_e32 v0, 0
	s_addc_u32 s34, s51, 0
	s_mov_b32 s35, -2
	s_waitcnt lgkmcnt(0)
	v_mov_b32_e32 v1, v0
	v_mov_b32_e32 v2, v0
	v_mov_b32_e32 v3, v0
	v_mov_b32_e32 v4, v0
	v_mov_b32_e32 v5, v0
	v_mov_b32_e32 v6, v0
	v_mov_b32_e32 v7, v0
	v_mov_b32_e32 v16, v0
	v_mov_b32_e32 v17, v0
	v_mov_b32_e32 v18, v0
	v_mov_b32_e32 v19, v0
	v_mov_b32_e32 v20, v0
	v_mov_b32_e32 v21, v0
	v_mov_b32_e32 v22, v0
	v_mov_b32_e32 v23, v0
	v_mov_b32_e32 v32, v0
	v_mov_b32_e32 v33, v0
	v_mov_b32_e32 v34, v0
	v_mov_b32_e32 v35, v0
	v_mov_b32_e32 v36, v0
	v_mov_b32_e32 v37, v0
	v_mov_b32_e32 v38, v0
	v_mov_b32_e32 v39, v0
	v_mov_b32_e32 v48, v0
	v_mov_b32_e32 v49, v0
	v_mov_b32_e32 v50, v0
	v_mov_b32_e32 v51, v0
	v_mov_b32_e32 v52, v0
	v_mov_b32_e32 v53, v0
	v_mov_b32_e32 v54, v0
	v_mov_b32_e32 v55, v0
	v_mov_b32_e32 v8, v0
	v_mov_b32_e32 v9, v0
	v_mov_b32_e32 v10, v0
	v_mov_b32_e32 v11, v0
	v_mov_b32_e32 v12, v0
	v_mov_b32_e32 v13, v0
	v_mov_b32_e32 v14, v0
	v_mov_b32_e32 v15, v0
	v_mov_b32_e32 v24, v0
	v_mov_b32_e32 v25, v0
	v_mov_b32_e32 v26, v0
	v_mov_b32_e32 v27, v0
	v_mov_b32_e32 v28, v0
	v_mov_b32_e32 v29, v0
	v_mov_b32_e32 v30, v0
	v_mov_b32_e32 v31, v0
	v_mov_b32_e32 v40, v0
	v_mov_b32_e32 v41, v0
	v_mov_b32_e32 v42, v0
	v_mov_b32_e32 v43, v0
	v_mov_b32_e32 v44, v0
	v_mov_b32_e32 v45, v0
	v_mov_b32_e32 v46, v0
	v_mov_b32_e32 v47, v0
	v_mov_b32_e32 v56, v0
	v_mov_b32_e32 v57, v0
	v_mov_b32_e32 v58, v0
	v_mov_b32_e32 v59, v0
	v_mov_b32_e32 v60, v0
	v_mov_b32_e32 v61, v0
	v_mov_b32_e32 v62, v0
	v_mov_b32_e32 v63, v0
	v_mov_b32_e32 v64, v0
	v_mov_b32_e32 v65, v0
	v_mov_b32_e32 v66, v0
	v_mov_b32_e32 v67, v0
	v_mov_b32_e32 v68, v0
	v_mov_b32_e32 v69, v0
	v_mov_b32_e32 v70, v0
	v_mov_b32_e32 v71, v0
	v_mov_b32_e32 v80, v0
	v_mov_b32_e32 v81, v0
	v_mov_b32_e32 v82, v0
	v_mov_b32_e32 v83, v0
	v_mov_b32_e32 v84, v0
	v_mov_b32_e32 v85, v0
	v_mov_b32_e32 v86, v0
	v_mov_b32_e32 v87, v0
	v_mov_b32_e32 v96, v0
	v_mov_b32_e32 v97, v0
	v_mov_b32_e32 v98, v0
	v_mov_b32_e32 v99, v0
	v_mov_b32_e32 v100, v0
	v_mov_b32_e32 v101, v0
	v_mov_b32_e32 v102, v0
	v_mov_b32_e32 v103, v0
	v_mov_b32_e32 v112, v0
	v_mov_b32_e32 v113, v0
	v_mov_b32_e32 v114, v0
	v_mov_b32_e32 v115, v0
	v_mov_b32_e32 v116, v0
	v_mov_b32_e32 v117, v0
	v_mov_b32_e32 v118, v0
	v_mov_b32_e32 v119, v0
	v_mov_b32_e32 v72, v0
	v_mov_b32_e32 v73, v0
	v_mov_b32_e32 v74, v0
	v_mov_b32_e32 v75, v0
	v_mov_b32_e32 v76, v0
	v_mov_b32_e32 v77, v0
	v_mov_b32_e32 v78, v0
	v_mov_b32_e32 v79, v0
	v_mov_b32_e32 v88, v0
	v_mov_b32_e32 v89, v0
	v_mov_b32_e32 v90, v0
	v_mov_b32_e32 v91, v0
	v_mov_b32_e32 v92, v0
	v_mov_b32_e32 v93, v0
	v_mov_b32_e32 v94, v0
	v_mov_b32_e32 v95, v0
	v_mov_b32_e32 v104, v0
	v_mov_b32_e32 v105, v0
	v_mov_b32_e32 v106, v0
	v_mov_b32_e32 v107, v0
	v_mov_b32_e32 v108, v0
	v_mov_b32_e32 v109, v0
	v_mov_b32_e32 v110, v0
	v_mov_b32_e32 v111, v0
	v_mov_b32_e32 v120, v0
	v_mov_b32_e32 v121, v0
	v_mov_b32_e32 v122, v0
	v_mov_b32_e32 v123, v0
	v_mov_b32_e32 v124, v0
	v_mov_b32_e32 v125, v0
	v_mov_b32_e32 v126, v0
	v_mov_b32_e32 v127, v0
	.p2alignl 6, 3212836864

; template <class Epi>
; __device__ __forceinline__ void gemm_phase(LAS unsigned char* lds, const Gemm g, const StaticOrder& S, const Epi& E) {
;     ...
;         const bool has_next = S.next(ui + 1, nxt);
;         const char* nA = has_next ? (const char*)g.A + (size_t)nxt.pm * tsA : cA; const char* nB = has_next ? (const char*)g.Bt + (size_t)nxt.pn * tsB : cB;
;         for (int t = 0; t < nt; t += 2) {
;             const bool last = (t == nt - 2);
;             if constexpr (Epi::HAS_MID) { if (t == nt1) E.mid(acc, cur, wr, wc, fr, fq); }
;             const char* a1 = cA + ((Epi::HAS_MID && t >= nt1) ? dA2 : 0) + (size_t)(t + 1) * kstep;
;             const char* a2 = last ? nA : cA + ((Epi::HAS_MID && t + 2 >= nt1) ? dA2 : 0) + (size_t)(t + 2) * kstep; const char* b2 = last ? nB : cB + ((Epi::HAS_MID && t + 2 >= nt1) ? dB2 : 0) + (size_t)(t + 2) * kstep;
;     ...
; #pragma unroll
;         for (int a = 0; a < 2; ++a)
; #pragma unroll
;             for (int b = 0; b < 2; ++b)
; #pragma unroll
;                 for (int m = 0; m < 4; ++m)
; #pragma unroll
;                     for (int n = 0; n < 2; ++n) acc[a][b][m][n] = (f32x4){0.f, 0.f, 0.f, 0.f};
;         cur = nxt; cA = nA; cB = nB; ++ui;
.LBB0_1349:
	s_ashr_i32 s25, s24, 31
	s_lshl_b64 s[26:27], s[24:25], 19
	s_add_u32 s26, s72, s26
	s_addc_u32 s27, s73, s27
	s_and_b64 s[34:35], s[6:7], exec
	s_cselect_b32 s25, s27, s39
	s_cselect_b32 s44, s26, s38
	s_ashr_i32 s15, s14, 31
	s_lshl_b64 s[34:35], s[14:15], 19
	v_readlane_b32 s15, v254, 25
	s_add_u32 s34, s15, s34
	v_readlane_b32 s15, v254, 26
	s_addc_u32 s35, s15, s35
	s_and_b64 s[42:43], s[6:7], exec
	s_cselect_b32 s15, s35, s41
	s_cselect_b32 s45, s34, s40
	s_add_u32 s38, s38, 0x40080
	s_addc_u32 s39, s39, 0
	s_add_u32 s46, s40, 0x100
	v_mov_b32_e32 v0, 0
	s_addc_u32 s47, s41, 0
	s_mov_b32 s48, -2
	v_mov_b32_e32 v1, v0
	v_mov_b32_e32 v2, v0
	v_mov_b32_e32 v3, v0
	v_mov_b32_e32 v4, v0
	v_mov_b32_e32 v5, v0
	v_mov_b32_e32 v6, v0
	v_mov_b32_e32 v7, v0
	v_mov_b32_e32 v16, v0
	v_mov_b32_e32 v17, v0
	v_mov_b32_e32 v18, v0
	v_mov_b32_e32 v19, v0
	v_mov_b32_e32 v20, v0
	v_mov_b32_e32 v21, v0
	v_mov_b32_e32 v22, v0
	v_mov_b32_e32 v23, v0
	v_mov_b32_e32 v32, v0
	v_mov_b32_e32 v33, v0
	v_mov_b32_e32 v34, v0
	v_mov_b32_e32 v35, v0
	v_mov_b32_e32 v36, v0
	v_mov_b32_e32 v37, v0
	v_mov_b32_e32 v38, v0
	v_mov_b32_e32 v39, v0
	v_mov_b32_e32 v48, v0
	v_mov_b32_e32 v49, v0
	v_mov_b32_e32 v50, v0
	v_mov_b32_e32 v51, v0
	v_mov_b32_e32 v52, v0
	v_mov_b32_e32 v53, v0
	v_mov_b32_e32 v54, v0
	v_mov_b32_e32 v55, v0
	v_mov_b32_e32 v8, v0
	v_mov_b32_e32 v9, v0
	v_mov_b32_e32 v10, v0
	v_mov_b32_e32 v11, v0
	v_mov_b32_e32 v12, v0
	v_mov_b32_e32 v13, v0
	v_mov_b32_e32 v14, v0
	v_mov_b32_e32 v15, v0
	v_mov_b32_e32 v24, v0
	v_mov_b32_e32 v25, v0
	v_mov_b32_e32 v26, v0
	v_mov_b32_e32 v27, v0
	v_mov_b32_e32 v28, v0
	v_mov_b32_e32 v29, v0
	v_mov_b32_e32 v30, v0
	v_mov_b32_e32 v31, v0
	v_mov_b32_e32 v40, v0
	v_mov_b32_e32 v41, v0
	v_mov_b32_e32 v42, v0
	v_mov_b32_e32 v43, v0
	v_mov_b32_e32 v44, v0
	v_mov_b32_e32 v45, v0
	v_mov_b32_e32 v46, v0
	v_mov_b32_e32 v47, v0
	v_mov_b32_e32 v56, v0
	v_mov_b32_e32 v57, v0
	v_mov_b32_e32 v58, v0
	v_mov_b32_e32 v59, v0
	v_mov_b32_e32 v60, v0
	v_mov_b32_e32 v61, v0
	v_mov_b32_e32 v62, v0
	v_mov_b32_e32 v63, v0
	v_mov_b32_e32 v64, v0
	v_mov_b32_e32 v65, v0
	v_mov_b32_e32 v66, v0
	v_mov_b32_e32 v67, v0
	v_mov_b32_e32 v68, v0
	v_mov_b32_e32 v69, v0
	v_mov_b32_e32 v70, v0
	v_mov_b32_e32 v71, v0
	v_mov_b32_e32 v80, v0
	v_mov_b32_e32 v81, v0
	v_mov_b32_e32 v82, v0
	v_mov_b32_e32 v83, v0
	v_mov_b32_e32 v84, v0
	v_mov_b32_e32 v85, v0
	v_mov_b32_e32 v86, v0
	v_mov_b32_e32 v87, v0
	v_mov_b32_e32 v96, v0
	v_mov_b32_e32 v97, v0
	v_mov_b32_e32 v98, v0
	v_mov_b32_e32 v99, v0
	v_mov_b32_e32 v100, v0
	v_mov_b32_e32 v101, v0
	v_mov_b32_e32 v102, v0
	v_mov_b32_e32 v103, v0
	v_mov_b32_e32 v112, v0
	v_mov_b32_e32 v113, v0
	v_mov_b32_e32 v114, v0
	v_mov_b32_e32 v115, v0
	v_mov_b32_e32 v116, v0
	v_mov_b32_e32 v117, v0
	v_mov_b32_e32 v118, v0
	v_mov_b32_e32 v119, v0
	v_mov_b32_e32 v72, v0
	v_mov_b32_e32 v73, v0
	v_mov_b32_e32 v74, v0
	v_mov_b32_e32 v75, v0
	v_mov_b32_e32 v76, v0
	v_mov_b32_e32 v77, v0
	v_mov_b32_e32 v78, v0
	v_mov_b32_e32 v79, v0
	v_mov_b32_e32 v88, v0
	v_mov_b32_e32 v89, v0
	v_mov_b32_e32 v90, v0
	v_mov_b32_e32 v91, v0
	v_mov_b32_e32 v92, v0
	v_mov_b32_e32 v93, v0
	v_mov_b32_e32 v94, v0
	v_mov_b32_e32 v95, v0
	v_mov_b32_e32 v104, v0
	v_mov_b32_e32 v105, v0
	v_mov_b32_e32 v106, v0
	v_mov_b32_e32 v107, v0
	v_mov_b32_e32 v108, v0
	v_mov_b32_e32 v109, v0
	v_mov_b32_e32 v110, v0
	v_mov_b32_e32 v111, v0
	v_mov_b32_e32 v120, v0
	v_mov_b32_e32 v121, v0
	v_mov_b32_e32 v122, v0
	v_mov_b32_e32 v123, v0
	v_mov_b32_e32 v124, v0
	v_mov_b32_e32 v125, v0
	v_mov_b32_e32 v126, v0
	v_mov_b32_e32 v127, v0
	.p2alignl 6, 3212836864

; template <class Epi>
; __device__ __forceinline__ void gemm_phase(LAS unsigned char* lds, const Gemm g, const StaticOrder& S, const Epi& E) {
;     ...
; #pragma unroll
;         for (int a = 0; a < 2; ++a)
; #pragma unroll
;             for (int b = 0; b < 2; ++b)
; #pragma unroll
;                 for (int m = 0; m < 4; ++m)
; #pragma unroll
;                     for (int n = 0; n < 2; ++n) acc[a][b][m][n] = (f32x4){0.f, 0.f, 0.f, 0.f};
;         cur = nxt; cA = nA; cB = nB; ++ui;
.LBB0_1432:
	s_add_u32 s25, s34, 0x100
	v_mov_b32_e32 v0, 0
	s_addc_u32 s50, s35, 0
	s_mov_b32 s51, -2
	v_mov_b32_e32 v1, v0
	v_mov_b32_e32 v2, v0
	v_mov_b32_e32 v3, v0
	v_mov_b32_e32 v4, v0
	v_mov_b32_e32 v5, v0
	v_mov_b32_e32 v6, v0
	v_mov_b32_e32 v7, v0
	v_mov_b32_e32 v16, v0
	v_mov_b32_e32 v17, v0
	v_mov_b32_e32 v18, v0
	v_mov_b32_e32 v19, v0
	v_mov_b32_e32 v20, v0
	v_mov_b32_e32 v21, v0
	v_mov_b32_e32 v22, v0
	v_mov_b32_e32 v23, v0
	v_mov_b32_e32 v32, v0
	v_mov_b32_e32 v33, v0
	v_mov_b32_e32 v34, v0
	v_mov_b32_e32 v35, v0
	v_mov_b32_e32 v36, v0
	v_mov_b32_e32 v37, v0
	v_mov_b32_e32 v38, v0
	v_mov_b32_e32 v39, v0
	v_mov_b32_e32 v48, v0
	v_mov_b32_e32 v49, v0
	v_mov_b32_e32 v50, v0
	v_mov_b32_e32 v51, v0
	v_mov_b32_e32 v52, v0
	v_mov_b32_e32 v53, v0
	v_mov_b32_e32 v54, v0
	v_mov_b32_e32 v55, v0
	v_mov_b32_e32 v8, v0
	v_mov_b32_e32 v9, v0
	v_mov_b32_e32 v10, v0
	v_mov_b32_e32 v11, v0
	v_mov_b32_e32 v12, v0
	v_mov_b32_e32 v13, v0
	v_mov_b32_e32 v14, v0
	v_mov_b32_e32 v15, v0
	v_mov_b32_e32 v24, v0
	v_mov_b32_e32 v25, v0
	v_mov_b32_e32 v26, v0
	v_mov_b32_e32 v27, v0
	v_mov_b32_e32 v28, v0
	v_mov_b32_e32 v29, v0
	v_mov_b32_e32 v30, v0
	v_mov_b32_e32 v31, v0
	v_mov_b32_e32 v40, v0
	v_mov_b32_e32 v41, v0
	v_mov_b32_e32 v42, v0
	v_mov_b32_e32 v43, v0
	v_mov_b32_e32 v44, v0
	v_mov_b32_e32 v45, v0
	v_mov_b32_e32 v46, v0
	v_mov_b32_e32 v47, v0
	v_mov_b32_e32 v56, v0
	v_mov_b32_e32 v57, v0
	v_mov_b32_e32 v58, v0
	v_mov_b32_e32 v59, v0
	v_mov_b32_e32 v60, v0
	v_mov_b32_e32 v61, v0
	v_mov_b32_e32 v62, v0
	v_mov_b32_e32 v63, v0
	v_mov_b32_e32 v64, v0
	v_mov_b32_e32 v65, v0
	v_mov_b32_e32 v66, v0
	v_mov_b32_e32 v67, v0
	v_mov_b32_e32 v68, v0
	v_mov_b32_e32 v69, v0
	v_mov_b32_e32 v70, v0
	v_mov_b32_e32 v71, v0
	v_mov_b32_e32 v80, v0
	v_mov_b32_e32 v81, v0
	v_mov_b32_e32 v82, v0
	v_mov_b32_e32 v83, v0
	v_mov_b32_e32 v84, v0
	v_mov_b32_e32 v85, v0
	v_mov_b32_e32 v86, v0
	v_mov_b32_e32 v87, v0
	v_mov_b32_e32 v96, v0
	v_mov_b32_e32 v97, v0
	v_mov_b32_e32 v98, v0
	v_mov_b32_e32 v99, v0
	v_mov_b32_e32 v100, v0
	v_mov_b32_e32 v101, v0
	v_mov_b32_e32 v102, v0
	v_mov_b32_e32 v103, v0
	v_mov_b32_e32 v112, v0
	v_mov_b32_e32 v113, v0
	v_mov_b32_e32 v114, v0
	v_mov_b32_e32 v115, v0
	v_mov_b32_e32 v116, v0
	v_mov_b32_e32 v117, v0
	v_mov_b32_e32 v118, v0
	v_mov_b32_e32 v119, v0
	v_mov_b32_e32 v72, v0
	v_mov_b32_e32 v73, v0
	v_mov_b32_e32 v74, v0
	v_mov_b32_e32 v75, v0
	v_mov_b32_e32 v76, v0
	v_mov_b32_e32 v77, v0
	v_mov_b32_e32 v78, v0
	v_mov_b32_e32 v79, v0
	v_mov_b32_e32 v88, v0
	v_mov_b32_e32 v89, v0
	v_mov_b32_e32 v90, v0
	v_mov_b32_e32 v91, v0
	v_mov_b32_e32 v92, v0
	v_mov_b32_e32 v93, v0
	v_mov_b32_e32 v94, v0
	v_mov_b32_e32 v95, v0
	v_mov_b32_e32 v104, v0
	v_mov_b32_e32 v105, v0
	v_mov_b32_e32 v106, v0
	v_mov_b32_e32 v107, v0
	v_mov_b32_e32 v108, v0
	v_mov_b32_e32 v109, v0
	v_mov_b32_e32 v110, v0
	v_mov_b32_e32 v111, v0
	v_mov_b32_e32 v120, v0
	v_mov_b32_e32 v121, v0
	v_mov_b32_e32 v122, v0
	v_mov_b32_e32 v123, v0
	v_mov_b32_e32 v124, v0
	v_mov_b32_e32 v125, v0
	v_mov_b32_e32 v126, v0
	v_mov_b32_e32 v127, v0
	.p2alignl 6, 3212836864
